# XCD-local seams made safe against the HID/R/U5/L16 buffer overlays: split barrier (XCD leaders arrive when the reads are done, the overwriting GEMM waits at its first epilogue)
# speedup vs baseline: 1.0095x; 1.0095x over previous
.LBB0_391:
	s_andn2_saveexec_b64 s[0:1], s[8:9]
	s_cbranch_execz .LBB0_411
	s_mov_b64 s[8:9], exec
	s_waitcnt lgkmcnt(0)
	s_mov_b64 s[8:9], exec
	v_mbcnt_lo_u32_b32 v0, s8, 0
	v_mbcnt_hi_u32_b32 v0, s9, v0
	v_cmp_eq_u32_e32 vcc, 0, v0
	s_waitcnt vmcnt(0)
	buffer_inv sc1
	s_and_saveexec_b64 s[10:11], vcc
	s_cbranch_execz .LBB0_410
	s_bcnt1_i32_b64 s0, s[8:9]
	v_mov_b32_e32 v0, 0x3800
	v_mov_b32_e32 v1, 1
	global_atomic_add v0, v1, s[40:41]
	v_mov_b32_e32 v0, 0x2000
	v_mov_b32_e32 v1, s0
	global_atomic_add v0, v1, s[6:7] offset:1024

.LBB0_412:
	s_mov_b32 s100, 0
	s_cmp_lt_i32 s42, 4
	s_cselect_b64 s[0:1], -1, 0
	s_cmp_gt_i32 s43, 3
	s_cselect_b64 s[2:3], -1, 0
	s_and_b64 s[0:1], s[0:1], s[2:3]
	s_andn2_b64 vcc, exec, s[0:1]
	s_cbranch_vccnz .LBB0_489
	v_mbcnt_hi_u32_b32 v8, -1, v210
	v_add_u32_e32 v9, s91, v8
	s_load_dword s0, s[88:89], 0x160
	s_add_u32 s10, s88, 0x160
	s_mov_b32 s1, s90
	s_addc_u32 s11, s89, 0
	s_mov_b64 s[4:5], s[88:89]
	s_waitcnt lgkmcnt(0)
	s_mov_b32 s2, s0
	s_cmpk_gt_i32 s1, 0x27f
	v_readfirstlane_b32 s23, v9
	s_cbranch_scc1 .LBB0_435
	v_lshlrev_b32_e32 v0, 4, v9
	v_add_u32_e32 v1, 0x2000, v0
	v_ashrrev_i32_e32 v2, 31, v1
	v_lshrrev_b32_e32 v2, 22, v2
	v_add_u32_e32 v2, v1, v2
	v_ashrrev_i32_e32 v10, 10, v2
	v_mul_i32_i24_e32 v2, 0x400, v10
	v_sub_u32_e32 v1, v1, v2
	v_lshrrev_b32_e32 v2, 4, v1
	v_bitop3_b32 v1, v2, v1, 32 bitop3:0x6c
	v_ashrrev_i32_e32 v2, 31, v1
	v_lshrrev_b32_e32 v2, 26, v2
	v_add_u32_e32 v2, v1, v2
	v_lshlrev_b32_e32 v3, 3, v10
	v_ashrrev_i32_e32 v11, 6, v2
	v_and_b32_e32 v3, -16, v3
	v_add_u32_e32 v3, v11, v3
	v_and_b32_e32 v4, 3, v11
	s_mov_b32 s6, 0x1fffe0
	v_lshrrev_b32_e32 v5, 2, v3
	v_lshlrev_b32_e32 v6, 1, v3
	v_and_b32_e32 v2, 0xc0, v2
	v_and_or_b32 v4, v3, s6, v4
	v_and_b32_e32 v5, 4, v5
	v_and_b32_e32 v6, 24, v6
	v_sub_u32_e32 v1, v1, v2
	v_mov_b32_e32 v2, 1
	v_or3_b32 v4, v4, v5, v6
	v_lshlrev_b32_e32 v5, 5, v10
	v_ashrrev_i16_sdwa v1, v2, sext(v1) dst_sel:DWORD dst_unused:UNUSED_PAD src0_sel:DWORD src1_sel:BYTE_0
	v_and_b32_e32 v5, 32, v5
	v_bfe_i32 v12, v1, 0, 16
	v_add_lshl_u32 v1, v5, v12, 1
	v_lshl_add_u32 v128, v4, 11, v1
	v_lshl_add_u32 v130, v3, 11, v1
	v_bfe_i32 v1, v9, 27, 1
	v_lshrrev_b32_e32 v1, 22, v1
	v_add_u32_e32 v1, v0, v1
	s_load_dwordx2 s[4:5], s[4:5], 0x150
	v_and_b32_e32 v1, 0xfffffc00, v1
	v_sub_u32_e32 v0, v0, v1
	v_lshrrev_b32_e32 v1, 4, v0
	v_ashrrev_i32_e32 v3, 31, v9
	v_bitop3_b32 v0, v1, v0, 32 bitop3:0x6c
	v_lshrrev_b32_e32 v3, 26, v3
	v_ashrrev_i32_e32 v1, 31, v0
	v_add_u32_e32 v3, v9, v3
	s_waitcnt lgkmcnt(0)
	s_add_u32 s3, s4, 0x2200000
	v_lshrrev_b32_e32 v1, 26, v1
	v_ashrrev_i32_e32 v14, 6, v3
	s_addc_u32 s25, s5, 0
	v_add_u32_e32 v1, v0, v1
	v_lshlrev_b32_e32 v3, 3, v14
	s_add_u32 s27, s4, 0x1480000
	v_ashrrev_i32_e32 v13, 6, v1
	v_and_b32_e32 v3, -16, v3
	s_addc_u32 s33, s5, 0
	v_add_u32_e32 v3, v13, v3
	v_and_b32_e32 v4, 3, v13
	s_ashr_i32 s37, s1, 31
	v_and_or_b32 v4, v3, s6, v4
	s_lshr_b32 s6, s37, 29
	s_add_i32 s6, s1, s6
	s_ashr_i32 s20, s23, 6
	s_ashr_i32 s7, s6, 3
	s_and_b32 s6, s6, -8
	s_ashr_i32 s24, s23, 8
	s_lshl_b32 s36, s20, 10
	s_sub_i32 s6, s1, s6
	s_cmp_lt_i32 s6, 0
	s_movk_i32 s50, 0x51
	s_cselect_b32 s8, s50, 0x50
	s_mul_i32 s6, s8, s6
	s_add_i32 s6, s6, s7
	s_mul_hi_i32 s7, s6, 0x66666667
	s_lshr_b32 s8, s7, 31
	s_ashr_i32 s7, s7, 5
	s_add_i32 s7, s7, s8
	s_lshl_b32 s8, s7, 3
	s_mulk_i32 s7, 0x50
	s_sub_i32 s6, s6, s7
	s_bfe_i32 s7, s6, 0x80000
	s_bfe_u32 s7, s7, 0x3000c
	s_add_i32 s7, s6, s7
	s_bfe_i32 s9, s7, 0x80000
	s_and_b32 s7, s7, 0xf8
	s_sub_i32 s6, s6, s7
	s_sext_i32_i16 s9, s9
	s_sext_i32_i8 s6, s6
	v_lshrrev_b32_e32 v5, 2, v3
	v_lshlrev_b32_e32 v6, 1, v3
	v_and_b32_e32 v1, 0xc0, v1
	s_lshr_b32 s22, s9, 3
	s_add_i32 s6, s8, s6
	v_and_b32_e32 v5, 4, v5
	v_and_b32_e32 v6, 24, v6
	v_sub_u32_e32 v0, v0, v1
	s_ashr_i32 s7, s6, 31
	s_bfe_i64 s[8:9], s[22:23], 0x100000
	v_or3_b32 v4, v4, v5, v6
	v_lshlrev_b32_e32 v5, 5, v14
	v_ashrrev_i16_sdwa v0, v2, sext(v0) dst_sel:DWORD dst_unused:UNUSED_PAD src0_sel:DWORD src1_sel:BYTE_0
	s_lshl_b64 s[12:13], s[6:7], 19
	s_lshl_b64 s[8:9], s[8:9], 19
	v_and_b32_e32 v5, 32, v5
	v_bfe_i32 v15, v0, 0, 16
	s_add_u32 s8, s27, s8
	v_add_lshl_u32 v0, v5, v15, 1
	s_addc_u32 s9, s33, s9
	s_add_i32 s51, s36, 0
	v_lshl_add_u32 v132, v4, 11, v0
	s_add_i32 m0, s51, 0x10000
	v_lshl_add_u32 v134, v3, 11, v0
	global_load_lds_dwordx4 v132, s[8:9]
	s_add_i32 m0, s51, 0x12000
	s_add_u32 s14, s8, 0x40000
	global_load_lds_dwordx4 v128, s[8:9]
	s_addc_u32 s15, s9, 0
	s_add_i32 m0, s51, 0x14000
	v_mov_b32_e32 v137, 0
	global_load_lds_dwordx4 v132, s[14:15]
	s_add_i32 m0, s51, 0x16000
	s_add_u32 s44, s3, s12
	s_addc_u32 s45, s25, s13
	s_add_i32 s52, s51, 0x2000
	global_load_lds_dwordx4 v128, s[14:15]
	s_mov_b32 m0, s51
	s_add_u32 s12, s44, 0x40000
	global_load_lds_dwordx4 v134, s[44:45]
	s_mov_b32 m0, s52
	s_addc_u32 s13, s45, 0
	s_add_i32 s53, s51, 0x4000
	global_load_lds_dwordx4 v130, s[44:45]
	s_mov_b32 m0, s53
	s_add_i32 s54, s51, 0x6000
	global_load_lds_dwordx4 v134, s[12:13]
	s_mov_b32 m0, s54
	v_mov_b32_e32 v133, v137
	global_load_lds_dwordx4 v130, s[12:13]
	v_mov_b32_e32 v129, v137
	v_mov_b32_e32 v135, v137
	v_mov_b32_e32 v131, v137
	s_cmp_eq_u32 s24, 1
	v_lshl_add_u64 v[6:7], s[8:9], 0, v[132:133]
	v_lshl_add_u64 v[4:5], s[8:9], 0, v[128:129]
	v_lshl_add_u64 v[0:1], s[44:45], 0, v[134:135]
	s_cselect_b64 s[12:13], -1, 0
	s_cmp_lg_u32 s24, 1
	v_lshl_add_u64 v[2:3], s[44:45], 0, v[130:131]
	s_cbranch_scc1 .LBB0_416
	s_barrier

.LBB0_425:
	s_cmp_lg_u32 s100, 0
	s_cbranch_scc1 .Lsw_done_4
	v_mov_b32_e32 v164, 0x23fc4
	ds_read_b32 v165, v164
	v_mov_b32_e32 v164, 0x3800
	s_waitcnt lgkmcnt(0)
	v_readfirstlane_b32 s99, v165
.Lsw_spin_4:
	global_load_dword v165, v164, s[40:41] sc1
	s_waitcnt vmcnt(0)
	v_readfirstlane_b32 s98, v165
	s_nop 1
	s_cmp_ge_u32 s98, s99
	s_cbranch_scc1 .Lsw_ok_4
	s_sleep 1
	s_branch .Lsw_spin_4
.Lsw_ok_4:
	s_mov_b32 s100, 1

.LBB0_1406:
	s_andn2_saveexec_b64 s[0:1], s[8:9]
	s_cbranch_execz .LBB0_1426
	s_mov_b64 s[8:9], exec
	s_waitcnt lgkmcnt(0)
	s_mov_b64 s[8:9], exec
	v_mbcnt_lo_u32_b32 v0, s8, 0
	v_mbcnt_hi_u32_b32 v0, s9, v0
	v_cmp_eq_u32_e32 vcc, 0, v0
	s_waitcnt vmcnt(0)
	buffer_inv sc1
	s_and_saveexec_b64 s[10:11], vcc
	s_cbranch_execz .LBB0_1425
	s_bcnt1_i32_b64 s0, s[8:9]
	v_mov_b32_e32 v0, 0x3900
	v_mov_b32_e32 v1, 1
	global_atomic_add v0, v1, s[40:41]
	v_mov_b32_e32 v0, 0x2000
	v_mov_b32_e32 v1, s0
	global_atomic_add v0, v1, s[6:7] offset:1024

.LBB0_1524:
	s_mov_b32 s100, 0
	s_cmp_lt_i32 s42, 11
	s_cselect_b64 s[0:1], -1, 0
	s_cmp_gt_i32 s43, 10
	s_cselect_b64 s[2:3], -1, 0
	s_and_b64 s[0:1], s[0:1], s[2:3]
	s_andn2_b64 vcc, exec, s[0:1]
	s_cbranch_vccnz .LBB0_1595
	v_mbcnt_hi_u32_b32 v8, -1, v210
	v_add_u32_e32 v9, s91, v8
	s_load_dword s0, s[88:89], 0x160
	s_waitcnt lgkmcnt(0)
	s_add_u32 s10, s88, 0x160
	s_mov_b32 s1, s90
	s_addc_u32 s11, s89, 0
	s_mov_b64 s[4:5], s[88:89]
	s_mov_b32 s2, s0
	s_cmpk_gt_i32 s1, 0x57f
	v_readfirstlane_b32 s19, v9
	s_cbranch_scc1 .LBB0_1541
	v_lshlrev_b32_e32 v0, 4, v9
	v_add_u32_e32 v1, 0x2000, v0
	v_ashrrev_i32_e32 v2, 31, v1
	v_lshrrev_b32_e32 v2, 22, v2
	v_add_u32_e32 v2, v1, v2
	v_ashrrev_i32_e32 v10, 10, v2
	v_mul_i32_i24_e32 v2, 0x400, v10
	v_sub_u32_e32 v1, v1, v2
	v_lshrrev_b32_e32 v2, 4, v1
	v_bitop3_b32 v1, v2, v1, 32 bitop3:0x6c
	v_ashrrev_i32_e32 v2, 31, v1
	v_lshrrev_b32_e32 v2, 26, v2
	v_add_u32_e32 v2, v1, v2
	v_lshlrev_b32_e32 v3, 3, v10
	v_ashrrev_i32_e32 v11, 6, v2
	v_and_b32_e32 v3, -16, v3
	v_add_u32_e32 v3, v11, v3
	v_and_b32_e32 v4, 3, v11
	s_mov_b32 s6, 0x1fffe0
	v_lshrrev_b32_e32 v5, 2, v3
	v_lshlrev_b32_e32 v6, 1, v3
	v_and_b32_e32 v2, 0xc0, v2
	v_and_or_b32 v4, v3, s6, v4
	v_and_b32_e32 v5, 4, v5
	v_and_b32_e32 v6, 24, v6
	v_sub_u32_e32 v1, v1, v2
	v_mov_b32_e32 v2, 1
	v_or3_b32 v4, v4, v5, v6
	v_lshlrev_b32_e32 v5, 5, v10
	v_ashrrev_i16_sdwa v1, v2, sext(v1) dst_sel:DWORD dst_unused:UNUSED_PAD src0_sel:DWORD src1_sel:BYTE_0
	v_and_b32_e32 v5, 32, v5
	v_bfe_i32 v12, v1, 0, 16
	v_add_lshl_u32 v1, v5, v12, 1
	v_lshl_add_u32 v128, v4, 11, v1
	v_lshl_add_u32 v130, v3, 11, v1
	v_bfe_i32 v1, v9, 27, 1
	v_lshrrev_b32_e32 v1, 22, v1
	v_add_u32_e32 v1, v0, v1
	s_load_dwordx2 s[4:5], s[4:5], 0x150
	v_and_b32_e32 v1, 0xfffffc00, v1
	v_sub_u32_e32 v0, v0, v1
	v_lshrrev_b32_e32 v1, 4, v0
	v_ashrrev_i32_e32 v3, 31, v9
	v_bitop3_b32 v0, v1, v0, 32 bitop3:0x6c
	v_lshrrev_b32_e32 v3, 26, v3
	v_ashrrev_i32_e32 v1, 31, v0
	v_add_u32_e32 v3, v9, v3
	s_waitcnt lgkmcnt(0)
	s_add_u32 s3, s4, 0x4200000
	v_lshrrev_b32_e32 v1, 26, v1
	v_ashrrev_i32_e32 v14, 6, v3
	s_addc_u32 s21, s5, 0
	v_add_u32_e32 v1, v0, v1
	v_lshlrev_b32_e32 v3, 3, v14
	s_add_u32 s23, s4, 0x1000000
	v_ashrrev_i32_e32 v13, 6, v1
	v_and_b32_e32 v3, -16, v3
	s_addc_u32 s33, s5, 0
	v_add_u32_e32 v3, v13, v3
	v_and_b32_e32 v4, 3, v13
	s_ashr_i32 s37, s1, 31
	v_and_or_b32 v4, v3, s6, v4
	s_lshr_b32 s6, s37, 29
	s_add_i32 s6, s1, s6
	s_ashr_i32 s16, s19, 6
	s_ashr_i32 s7, s6, 3
	s_and_b32 s6, s6, -8
	s_ashr_i32 s20, s19, 8
	s_lshl_b32 s36, s16, 10
	s_sub_i32 s6, s1, s6
	s_cmp_lt_i32 s6, 0
	s_movk_i32 s44, 0xb1
	s_cselect_b32 s8, s44, 0xb0
	s_mul_i32 s6, s8, s6
	s_add_i32 s6, s6, s7
	s_mul_hi_i32 s7, s6, 0x2e8ba2e9
	s_lshr_b32 s8, s7, 31
	s_ashr_i32 s7, s7, 5
	s_add_i32 s7, s7, s8
	s_lshl_b32 s8, s7, 3
	s_mulk_i32 s7, 0xb0
	s_sub_i32 s6, s6, s7
	s_bfe_u32 s7, s6, 0x3001c
	s_add_i32 s7, s6, s7
	s_sext_i32_i16 s9, s7
	s_and_b32 s7, s7, 0xfff8
	s_sub_i32 s6, s6, s7
	s_sext_i32_i16 s6, s6
	v_lshrrev_b32_e32 v5, 2, v3
	v_lshlrev_b32_e32 v6, 1, v3
	v_and_b32_e32 v1, 0xc0, v1
	s_lshr_b32 s18, s9, 3
	s_add_i32 s6, s8, s6
	v_and_b32_e32 v5, 4, v5
	v_and_b32_e32 v6, 24, v6
	v_sub_u32_e32 v0, v0, v1
	s_ashr_i32 s7, s6, 31
	s_bfe_i64 s[8:9], s[18:19], 0x100000
	v_or3_b32 v4, v4, v5, v6
	v_lshlrev_b32_e32 v5, 5, v14
	v_ashrrev_i16_sdwa v0, v2, sext(v0) dst_sel:DWORD dst_unused:UNUSED_PAD src0_sel:DWORD src1_sel:BYTE_0
	s_lshl_b64 s[12:13], s[6:7], 19
	s_lshl_b64 s[8:9], s[8:9], 19
	v_and_b32_e32 v5, 32, v5
	v_bfe_i32 v15, v0, 0, 16
	s_add_u32 s8, s23, s8
	v_add_lshl_u32 v0, v5, v15, 1
	s_addc_u32 s9, s33, s9
	s_add_i32 s45, s36, 0
	v_lshl_add_u32 v132, v4, 11, v0
	s_add_i32 m0, s45, 0x10000
	v_lshl_add_u32 v134, v3, 11, v0
	global_load_lds_dwordx4 v132, s[8:9]
	s_add_i32 m0, s45, 0x12000
	s_add_u32 s14, s8, 0x40000
	global_load_lds_dwordx4 v128, s[8:9]
	s_addc_u32 s15, s9, 0
	s_add_i32 m0, s45, 0x14000
	v_mov_b32_e32 v133, 0
	global_load_lds_dwordx4 v132, s[14:15]
	s_add_i32 m0, s45, 0x16000
	s_add_u32 s34, s3, s12
	s_addc_u32 s35, s21, s13
	s_add_i32 s46, s45, 0x2000
	global_load_lds_dwordx4 v128, s[14:15]
	s_mov_b32 m0, s45
	s_add_u32 s12, s34, 0x40000
	global_load_lds_dwordx4 v134, s[34:35]
	s_mov_b32 m0, s46
	s_addc_u32 s13, s35, 0
	s_add_i32 s47, s45, 0x4000
	global_load_lds_dwordx4 v130, s[34:35]
	s_mov_b32 m0, s47
	s_add_i32 s48, s45, 0x6000
	global_load_lds_dwordx4 v134, s[12:13]
	s_mov_b32 m0, s48
	v_mov_b32_e32 v129, v133
	global_load_lds_dwordx4 v130, s[12:13]
	v_mov_b32_e32 v135, v133
	v_mov_b32_e32 v131, v133
	s_cmp_eq_u32 s20, 1
	v_lshl_add_u64 v[6:7], s[8:9], 0, v[132:133]
	v_lshl_add_u64 v[4:5], s[8:9], 0, v[128:129]
	v_lshl_add_u64 v[0:1], s[34:35], 0, v[134:135]
	s_cselect_b64 s[12:13], -1, 0
	s_cmp_lg_u32 s20, 1
	v_lshl_add_u64 v[2:3], s[34:35], 0, v[130:131]
	s_cbranch_scc1 .LBB0_1528
	s_barrier

.LBB0_1537:
	s_cmp_lg_u32 s100, 0
	s_cbranch_scc1 .Lsw_done_11
	v_mov_b32_e32 v170, 0x23fc4
	ds_read_b32 v171, v170
	v_mov_b32_e32 v170, 0x3900
	s_waitcnt lgkmcnt(0)
	v_readfirstlane_b32 s99, v171
.Lsw_spin_11:
	global_load_dword v171, v170, s[40:41] sc1
	s_waitcnt vmcnt(0)
	v_readfirstlane_b32 s98, v171
	s_nop 1
	s_cmp_ge_u32 s98, s99
	s_cbranch_scc1 .Lsw_ok_11
	s_sleep 1
	s_branch .Lsw_spin_11

.LBB0_2100:
	s_andn2_saveexec_b64 s[0:1], s[8:9]
	s_cbranch_execz .LBB0_2120
	s_mov_b64 s[8:9], exec
	s_waitcnt lgkmcnt(0)
	s_mov_b64 s[8:9], exec
	v_mbcnt_lo_u32_b32 v0, s8, 0
	v_mbcnt_hi_u32_b32 v0, s9, v0
	v_cmp_eq_u32_e32 vcc, 0, v0
	s_waitcnt vmcnt(0)
	buffer_inv sc1
	s_and_saveexec_b64 s[10:11], vcc
	s_cbranch_execz .LBB0_2119
	s_bcnt1_i32_b64 s0, s[8:9]
	v_mov_b32_e32 v0, 0x3a00
	v_mov_b32_e32 v1, 1
	global_atomic_add v0, v1, s[40:41]
	v_mov_b32_e32 v0, 0x2000
	v_mov_b32_e32 v1, s0
	global_atomic_add v0, v1, s[6:7] offset:1024

.LBB0_2121:
	s_mov_b32 s100, 0
	s_cmp_lt_i32 s42, 16
	s_cselect_b64 s[0:1], -1, 0
	s_cmp_gt_i32 s43, 15
	s_cselect_b64 s[2:3], -1, 0
	s_and_b64 s[0:1], s[0:1], s[2:3]
	s_andn2_b64 vcc, exec, s[0:1]
	s_cbranch_vccnz .LBB0_2198
	v_mbcnt_hi_u32_b32 v8, -1, v210
	v_add_u32_e32 v9, s91, v8
	s_load_dword s0, s[88:89], 0x160
	s_waitcnt lgkmcnt(0)
	s_add_u32 s10, s88, 0x160
	s_mov_b32 s1, s90
	s_addc_u32 s11, s89, 0
	s_mov_b64 s[4:5], s[88:89]
	s_mov_b32 s2, s0
	s_cmpk_gt_i32 s1, 0x27f
	v_readfirstlane_b32 s23, v9
	s_cbranch_scc1 .LBB0_2144
	v_lshlrev_b32_e32 v0, 4, v9
	v_add_u32_e32 v1, 0x2000, v0
	v_ashrrev_i32_e32 v2, 31, v1
	v_lshrrev_b32_e32 v2, 22, v2
	v_add_u32_e32 v2, v1, v2
	v_ashrrev_i32_e32 v10, 10, v2
	v_mul_i32_i24_e32 v2, 0x400, v10
	v_sub_u32_e32 v1, v1, v2
	v_lshrrev_b32_e32 v2, 4, v1
	v_bitop3_b32 v1, v2, v1, 32 bitop3:0x6c
	v_ashrrev_i32_e32 v2, 31, v1
	v_lshrrev_b32_e32 v2, 26, v2
	v_add_u32_e32 v2, v1, v2
	v_lshlrev_b32_e32 v3, 3, v10
	v_ashrrev_i32_e32 v11, 6, v2
	v_and_b32_e32 v3, -16, v3
	v_add_u32_e32 v3, v11, v3
	v_and_b32_e32 v4, 3, v11
	s_mov_b32 s6, 0x1fffe0
	v_lshrrev_b32_e32 v5, 2, v3
	v_lshlrev_b32_e32 v6, 1, v3
	v_and_b32_e32 v2, 0xc0, v2
	v_and_or_b32 v4, v3, s6, v4
	v_and_b32_e32 v5, 4, v5
	v_and_b32_e32 v6, 24, v6
	v_sub_u32_e32 v1, v1, v2
	v_mov_b32_e32 v2, 1
	v_or3_b32 v4, v4, v5, v6
	v_lshlrev_b32_e32 v5, 5, v10
	v_ashrrev_i16_sdwa v1, v2, sext(v1) dst_sel:DWORD dst_unused:UNUSED_PAD src0_sel:DWORD src1_sel:BYTE_0
	v_and_b32_e32 v5, 32, v5
	v_bfe_i32 v12, v1, 0, 16
	v_add_lshl_u32 v1, v5, v12, 1
	v_lshl_add_u32 v128, v4, 11, v1
	v_lshl_add_u32 v130, v3, 11, v1
	v_bfe_i32 v1, v9, 27, 1
	v_lshrrev_b32_e32 v1, 22, v1
	v_add_u32_e32 v1, v0, v1
	s_load_dwordx2 s[4:5], s[4:5], 0x150
	v_and_b32_e32 v1, 0xfffffc00, v1
	v_sub_u32_e32 v0, v0, v1
	v_lshrrev_b32_e32 v1, 4, v0
	v_ashrrev_i32_e32 v3, 31, v9
	v_bitop3_b32 v0, v1, v0, 32 bitop3:0x6c
	v_lshrrev_b32_e32 v3, 26, v3
	v_ashrrev_i32_e32 v1, 31, v0
	v_add_u32_e32 v3, v9, v3
	s_waitcnt lgkmcnt(0)
	s_add_u32 s3, s4, 0x2200000
	v_lshrrev_b32_e32 v1, 26, v1
	v_ashrrev_i32_e32 v14, 6, v3
	s_addc_u32 s25, s5, 0
	v_add_u32_e32 v1, v0, v1
	v_lshlrev_b32_e32 v3, 3, v14
	s_add_u32 s27, s4, 0x1480000
	v_ashrrev_i32_e32 v13, 6, v1
	v_and_b32_e32 v3, -16, v3
	s_addc_u32 s33, s5, 0
	v_add_u32_e32 v3, v13, v3
	v_and_b32_e32 v4, 3, v13
	s_ashr_i32 s37, s1, 31
	v_and_or_b32 v4, v3, s6, v4
	s_lshr_b32 s6, s37, 29
	s_add_i32 s6, s1, s6
	s_ashr_i32 s20, s23, 6
	s_ashr_i32 s7, s6, 3
	s_and_b32 s6, s6, -8
	s_ashr_i32 s24, s23, 8
	s_lshl_b32 s36, s20, 10
	s_sub_i32 s6, s1, s6
	s_cmp_lt_i32 s6, 0
	s_movk_i32 s50, 0x51
	s_cselect_b32 s8, s50, 0x50
	s_mul_i32 s6, s8, s6
	s_add_i32 s6, s6, s7
	s_mul_hi_i32 s7, s6, 0x66666667
	s_lshr_b32 s8, s7, 31
	s_ashr_i32 s7, s7, 5
	s_add_i32 s7, s7, s8
	s_lshl_b32 s8, s7, 3
	s_mulk_i32 s7, 0x50
	s_sub_i32 s6, s6, s7
	s_bfe_i32 s7, s6, 0x80000
	s_bfe_u32 s7, s7, 0x3000c
	s_add_i32 s7, s6, s7
	s_bfe_i32 s9, s7, 0x80000
	s_and_b32 s7, s7, 0xf8
	s_sub_i32 s6, s6, s7
	s_sext_i32_i16 s9, s9
	s_sext_i32_i8 s6, s6
	v_lshrrev_b32_e32 v5, 2, v3
	v_lshlrev_b32_e32 v6, 1, v3
	v_and_b32_e32 v1, 0xc0, v1
	s_lshr_b32 s22, s9, 3
	s_add_i32 s6, s8, s6
	v_and_b32_e32 v5, 4, v5
	v_and_b32_e32 v6, 24, v6
	v_sub_u32_e32 v0, v0, v1
	s_ashr_i32 s7, s6, 31
	s_bfe_i64 s[8:9], s[22:23], 0x100000
	v_or3_b32 v4, v4, v5, v6
	v_lshlrev_b32_e32 v5, 5, v14
	v_ashrrev_i16_sdwa v0, v2, sext(v0) dst_sel:DWORD dst_unused:UNUSED_PAD src0_sel:DWORD src1_sel:BYTE_0
	s_lshl_b64 s[12:13], s[6:7], 19
	s_lshl_b64 s[8:9], s[8:9], 19
	v_and_b32_e32 v5, 32, v5
	v_bfe_i32 v15, v0, 0, 16
	s_add_u32 s8, s27, s8
	v_add_lshl_u32 v0, v5, v15, 1
	s_addc_u32 s9, s33, s9
	s_add_i32 s51, s36, 0
	v_lshl_add_u32 v132, v4, 11, v0
	s_add_i32 m0, s51, 0x10000
	v_lshl_add_u32 v134, v3, 11, v0
	global_load_lds_dwordx4 v132, s[8:9]
	s_add_i32 m0, s51, 0x12000
	s_add_u32 s14, s8, 0x40000
	global_load_lds_dwordx4 v128, s[8:9]
	s_addc_u32 s15, s9, 0
	s_add_i32 m0, s51, 0x14000
	v_mov_b32_e32 v137, 0
	global_load_lds_dwordx4 v132, s[14:15]
	s_add_i32 m0, s51, 0x16000
	s_add_u32 s44, s3, s12
	s_addc_u32 s45, s25, s13
	s_add_i32 s52, s51, 0x2000
	global_load_lds_dwordx4 v128, s[14:15]
	s_mov_b32 m0, s51
	s_add_u32 s12, s44, 0x40000
	global_load_lds_dwordx4 v134, s[44:45]
	s_mov_b32 m0, s52
	s_addc_u32 s13, s45, 0
	s_add_i32 s53, s51, 0x4000
	global_load_lds_dwordx4 v130, s[44:45]
	s_mov_b32 m0, s53
	s_add_i32 s54, s51, 0x6000
	global_load_lds_dwordx4 v134, s[12:13]
	s_mov_b32 m0, s54
	v_mov_b32_e32 v133, v137
	global_load_lds_dwordx4 v130, s[12:13]
	v_mov_b32_e32 v129, v137
	v_mov_b32_e32 v135, v137
	v_mov_b32_e32 v131, v137
	s_cmp_eq_u32 s24, 1
	v_lshl_add_u64 v[6:7], s[8:9], 0, v[132:133]
	v_lshl_add_u64 v[4:5], s[8:9], 0, v[128:129]
	v_lshl_add_u64 v[0:1], s[44:45], 0, v[134:135]
	s_cselect_b64 s[12:13], -1, 0
	s_cmp_lg_u32 s24, 1
	v_lshl_add_u64 v[2:3], s[44:45], 0, v[130:131]
	s_cbranch_scc1 .LBB0_2125
	s_barrier

.LBB0_2134:
	s_cmp_lg_u32 s100, 0
	s_cbranch_scc1 .Lsw_done_16
	v_mov_b32_e32 v164, 0x23fc4
	ds_read_b32 v165, v164
	v_mov_b32_e32 v164, 0x3a00
	s_waitcnt lgkmcnt(0)
	v_readfirstlane_b32 s99, v165

.LBB0_3112:
	s_andn2_saveexec_b64 s[0:1], s[8:9]
	s_cbranch_execz .LBB0_3132
	s_mov_b64 s[8:9], exec
	s_waitcnt lgkmcnt(0)
	s_mov_b64 s[8:9], exec
	v_mbcnt_lo_u32_b32 v0, s8, 0
	v_mbcnt_hi_u32_b32 v0, s9, v0
	v_cmp_eq_u32_e32 vcc, 0, v0
	s_waitcnt vmcnt(0)
	buffer_inv sc1
	s_and_saveexec_b64 s[10:11], vcc
	s_cbranch_execz .LBB0_3131
	s_bcnt1_i32_b64 s0, s[8:9]
	v_mov_b32_e32 v0, 0x3b00
	v_mov_b32_e32 v1, 1
	global_atomic_add v0, v1, s[40:41]
	v_mov_b32_e32 v0, 0x2000
	v_mov_b32_e32 v1, s0
	global_atomic_add v0, v1, s[6:7] offset:1024

.LBB0_3230:
	s_mov_b32 s100, 0
	s_cmp_lt_i32 s42, 23
	s_cselect_b64 s[0:1], -1, 0
	s_cmp_gt_i32 s43, 22
	s_cselect_b64 s[2:3], -1, 0
	s_and_b64 s[0:1], s[0:1], s[2:3]
	s_andn2_b64 vcc, exec, s[0:1]
	s_cbranch_vccnz .LBB0_3301
	v_mbcnt_hi_u32_b32 v8, -1, v210
	v_add_u32_e32 v9, s91, v8
	s_load_dword s0, s[88:89], 0x160
	s_waitcnt lgkmcnt(0)
	s_add_u32 s10, s88, 0x160
	s_mov_b32 s1, s90
	s_addc_u32 s11, s89, 0
	s_mov_b64 s[4:5], s[88:89]
	s_mov_b32 s2, s0
	s_cmpk_gt_i32 s1, 0x57f
	v_readfirstlane_b32 s19, v9
	s_cbranch_scc1 .LBB0_3247
	v_lshlrev_b32_e32 v0, 4, v9
	v_add_u32_e32 v1, 0x2000, v0
	v_ashrrev_i32_e32 v2, 31, v1
	v_lshrrev_b32_e32 v2, 22, v2
	v_add_u32_e32 v2, v1, v2
	v_ashrrev_i32_e32 v10, 10, v2
	v_mul_i32_i24_e32 v2, 0x400, v10
	v_sub_u32_e32 v1, v1, v2
	v_lshrrev_b32_e32 v2, 4, v1
	v_bitop3_b32 v1, v2, v1, 32 bitop3:0x6c
	v_ashrrev_i32_e32 v2, 31, v1
	v_lshrrev_b32_e32 v2, 26, v2
	v_add_u32_e32 v2, v1, v2
	v_lshlrev_b32_e32 v3, 3, v10
	v_ashrrev_i32_e32 v11, 6, v2
	v_and_b32_e32 v3, -16, v3
	v_add_u32_e32 v3, v11, v3
	v_and_b32_e32 v4, 3, v11
	s_mov_b32 s6, 0x1fffe0
	v_lshrrev_b32_e32 v5, 2, v3
	v_lshlrev_b32_e32 v6, 1, v3
	v_and_b32_e32 v2, 0xc0, v2
	v_and_or_b32 v4, v3, s6, v4
	v_and_b32_e32 v5, 4, v5
	v_and_b32_e32 v6, 24, v6
	v_sub_u32_e32 v1, v1, v2
	v_mov_b32_e32 v2, 1
	v_or3_b32 v4, v4, v5, v6
	v_lshlrev_b32_e32 v5, 5, v10
	v_ashrrev_i16_sdwa v1, v2, sext(v1) dst_sel:DWORD dst_unused:UNUSED_PAD src0_sel:DWORD src1_sel:BYTE_0
	v_and_b32_e32 v5, 32, v5
	v_bfe_i32 v12, v1, 0, 16
	v_add_lshl_u32 v1, v5, v12, 1
	v_lshl_add_u32 v128, v4, 11, v1
	v_lshl_add_u32 v130, v3, 11, v1
	v_bfe_i32 v1, v9, 27, 1
	v_lshrrev_b32_e32 v1, 22, v1
	v_add_u32_e32 v1, v0, v1
	s_load_dwordx2 s[4:5], s[4:5], 0x150
	v_and_b32_e32 v1, 0xfffffc00, v1
	v_sub_u32_e32 v0, v0, v1
	v_lshrrev_b32_e32 v1, 4, v0
	v_ashrrev_i32_e32 v3, 31, v9
	v_bitop3_b32 v0, v1, v0, 32 bitop3:0x6c
	v_lshrrev_b32_e32 v3, 26, v3
	v_ashrrev_i32_e32 v1, 31, v0
	v_add_u32_e32 v3, v9, v3
	s_waitcnt lgkmcnt(0)
	s_add_u32 s3, s4, 0x4200000
	v_lshrrev_b32_e32 v1, 26, v1
	v_ashrrev_i32_e32 v14, 6, v3
	s_addc_u32 s21, s5, 0
	v_add_u32_e32 v1, v0, v1
	v_lshlrev_b32_e32 v3, 3, v14
	s_add_u32 s23, s4, 0x1000000
	v_ashrrev_i32_e32 v13, 6, v1
	v_and_b32_e32 v3, -16, v3
	s_addc_u32 s33, s5, 0
	v_add_u32_e32 v3, v13, v3
	v_and_b32_e32 v4, 3, v13
	s_ashr_i32 s37, s1, 31
	v_and_or_b32 v4, v3, s6, v4
	s_lshr_b32 s6, s37, 29
	s_add_i32 s6, s1, s6
	s_ashr_i32 s16, s19, 6
	s_ashr_i32 s7, s6, 3
	s_and_b32 s6, s6, -8
	s_ashr_i32 s20, s19, 8
	s_lshl_b32 s36, s16, 10
	s_sub_i32 s6, s1, s6
	s_cmp_lt_i32 s6, 0
	s_movk_i32 s44, 0xb1
	s_cselect_b32 s8, s44, 0xb0
	s_mul_i32 s6, s8, s6
	s_add_i32 s6, s6, s7
	s_mul_hi_i32 s7, s6, 0x2e8ba2e9
	s_lshr_b32 s8, s7, 31
	s_ashr_i32 s7, s7, 5
	s_add_i32 s7, s7, s8
	s_lshl_b32 s8, s7, 3
	s_mulk_i32 s7, 0xb0
	s_sub_i32 s6, s6, s7
	s_bfe_u32 s7, s6, 0x3001c
	s_add_i32 s7, s6, s7
	s_sext_i32_i16 s9, s7
	s_and_b32 s7, s7, 0xfff8
	s_sub_i32 s6, s6, s7
	s_sext_i32_i16 s6, s6
	v_lshrrev_b32_e32 v5, 2, v3
	v_lshlrev_b32_e32 v6, 1, v3
	v_and_b32_e32 v1, 0xc0, v1
	s_lshr_b32 s18, s9, 3
	s_add_i32 s6, s8, s6
	v_and_b32_e32 v5, 4, v5
	v_and_b32_e32 v6, 24, v6
	v_sub_u32_e32 v0, v0, v1
	s_ashr_i32 s7, s6, 31
	s_bfe_i64 s[8:9], s[18:19], 0x100000
	v_or3_b32 v4, v4, v5, v6
	v_lshlrev_b32_e32 v5, 5, v14
	v_ashrrev_i16_sdwa v0, v2, sext(v0) dst_sel:DWORD dst_unused:UNUSED_PAD src0_sel:DWORD src1_sel:BYTE_0
	s_lshl_b64 s[12:13], s[6:7], 19
	s_lshl_b64 s[8:9], s[8:9], 19
	v_and_b32_e32 v5, 32, v5
	v_bfe_i32 v15, v0, 0, 16
	s_add_u32 s8, s23, s8
	v_add_lshl_u32 v0, v5, v15, 1
	s_addc_u32 s9, s33, s9
	s_add_i32 s45, s36, 0
	v_lshl_add_u32 v132, v4, 11, v0
	s_add_i32 m0, s45, 0x10000
	v_lshl_add_u32 v134, v3, 11, v0
	global_load_lds_dwordx4 v132, s[8:9]
	s_add_i32 m0, s45, 0x12000
	s_add_u32 s14, s8, 0x40000
	global_load_lds_dwordx4 v128, s[8:9]
	s_addc_u32 s15, s9, 0
	s_add_i32 m0, s45, 0x14000
	v_mov_b32_e32 v133, 0
	global_load_lds_dwordx4 v132, s[14:15]
	s_add_i32 m0, s45, 0x16000
	s_add_u32 s34, s3, s12
	s_addc_u32 s35, s21, s13
	s_add_i32 s46, s45, 0x2000
	global_load_lds_dwordx4 v128, s[14:15]
	s_mov_b32 m0, s45
	s_add_u32 s12, s34, 0x40000
	global_load_lds_dwordx4 v134, s[34:35]
	s_mov_b32 m0, s46
	s_addc_u32 s13, s35, 0
	s_add_i32 s47, s45, 0x4000
	global_load_lds_dwordx4 v130, s[34:35]
	s_mov_b32 m0, s47
	s_add_i32 s48, s45, 0x6000
	global_load_lds_dwordx4 v134, s[12:13]
	s_mov_b32 m0, s48
	v_mov_b32_e32 v129, v133
	global_load_lds_dwordx4 v130, s[12:13]
	v_mov_b32_e32 v135, v133
	v_mov_b32_e32 v131, v133
	s_cmp_eq_u32 s20, 1
	v_lshl_add_u64 v[6:7], s[8:9], 0, v[132:133]
	v_lshl_add_u64 v[4:5], s[8:9], 0, v[128:129]
	v_lshl_add_u64 v[0:1], s[34:35], 0, v[134:135]
	s_cselect_b64 s[12:13], -1, 0
	s_cmp_lg_u32 s20, 1
	v_lshl_add_u64 v[2:3], s[34:35], 0, v[130:131]
	s_cbranch_scc1 .LBB0_3234
	s_barrier

.LBB0_3243:
	s_cmp_lg_u32 s100, 0
	s_cbranch_scc1 .Lsw_done_23
	v_mov_b32_e32 v170, 0x23fc4
	ds_read_b32 v171, v170
	v_mov_b32_e32 v170, 0x3b00
	s_waitcnt lgkmcnt(0)
	v_readfirstlane_b32 s99, v171

	.amdhsa_kernel _Z6mk_fwd4Args
		.amdhsa_group_segment_fixed_size 0
		.amdhsa_private_segment_fixed_size 0
		.amdhsa_kernarg_size 608
		.amdhsa_user_sgpr_count 2
		.amdhsa_user_sgpr_dispatch_ptr 0
		.amdhsa_user_sgpr_queue_ptr 0
		.amdhsa_user_sgpr_kernarg_segment_ptr 1
		.amdhsa_user_sgpr_dispatch_id 0
		.amdhsa_user_sgpr_kernarg_preload_length 0
		.amdhsa_user_sgpr_kernarg_preload_offset 0
		.amdhsa_user_sgpr_private_segment_size 0
		.amdhsa_uses_dynamic_stack 0
		.amdhsa_enable_private_segment 0
		.amdhsa_system_sgpr_workgroup_id_x 1
		.amdhsa_system_sgpr_workgroup_id_y 0
		.amdhsa_system_sgpr_workgroup_id_z 0
		.amdhsa_system_sgpr_workgroup_info 0
		.amdhsa_system_vgpr_workitem_id 2
		.amdhsa_next_free_vgpr 255
		.amdhsa_next_free_sgpr 102
		.amdhsa_accum_offset 256
		.amdhsa_reserve_vcc 1
		.amdhsa_float_round_mode_32 0
		.amdhsa_float_round_mode_16_64 0
		.amdhsa_float_denorm_mode_32 3
		.amdhsa_float_denorm_mode_16_64 3
		.amdhsa_dx10_clamp 1
		.amdhsa_ieee_mode 1
		.amdhsa_fp16_overflow 0
		.amdhsa_tg_split 0
		.amdhsa_exception_fp_ieee_invalid_op 0
		.amdhsa_exception_fp_denorm_src 0
		.amdhsa_exception_fp_ieee_div_zero 0
		.amdhsa_exception_fp_ieee_overflow 0
		.amdhsa_exception_fp_ieee_underflow 0
		.amdhsa_exception_fp_ieee_inexact 0
		.amdhsa_exception_int_div_zero 0
	.end_amdhsa_kernel

amdhsa.kernels:
  - .agpr_count:     0
    .args:
      - .offset:         0
        .size:           352
        .value_kind:     by_value
      - .offset:         352
        .size:           4
        .value_kind:     hidden_block_count_x
      - .offset:         356
        .size:           4
        .value_kind:     hidden_block_count_y
      - .offset:         360
        .size:           4
        .value_kind:     hidden_block_count_z
      - .offset:         364
        .size:           2
        .value_kind:     hidden_group_size_x
      - .offset:         366
        .size:           2
        .value_kind:     hidden_group_size_y
      - .offset:         368
        .size:           2
        .value_kind:     hidden_group_size_z
      - .offset:         370
        .size:           2
        .value_kind:     hidden_remainder_x
      - .offset:         372
        .size:           2
        .value_kind:     hidden_remainder_y
      - .offset:         374
        .size:           2
        .value_kind:     hidden_remainder_z
      - .offset:         392
        .size:           8
        .value_kind:     hidden_global_offset_x
      - .offset:         400
        .size:           8
        .value_kind:     hidden_global_offset_y
      - .offset:         408
        .size:           8
        .value_kind:     hidden_global_offset_z
      - .offset:         416
        .size:           2
        .value_kind:     hidden_grid_dims
      - .offset:         440
        .size:           8
        .value_kind:     hidden_multigrid_sync_arg
      - .offset:         472
        .size:           4
        .value_kind:     hidden_dynamic_lds_size
    .group_segment_fixed_size: 0
    .kernarg_segment_align: 8
    .kernarg_segment_size: 608
    .language:       OpenCL C
    .language_version:
      - 2
      - 0
    .max_flat_workgroup_size: 512
    .name:           _Z6mk_fwd4Args
    .private_segment_fixed_size: 0
    .sgpr_count:     108
    .sgpr_spill_count: 11
    .symbol:         _Z6mk_fwd4Args.kd
    .uniform_work_group_size: 1
    .uses_dynamic_stack: false
    .vgpr_count:     255
    .vgpr_spill_count: 0
    .wavefront_size: 64
